# moba_kv tile loop: Q-prefetch waits and copies moved ahead of the 17 output stores (they no longer drain the stores)
# speedup vs baseline: 1.0020x; 1.0020x over previous
; __device__ __forceinline__ void moba_kv_item(LAS unsigned char* lds, const Ptrs& P, int bh, int n, int part, bool split) {
;     ...
;     for (int qt = wid; qt < ntile; qt += 8) {
;         const bool valid = vn; const unsigned e = en;
;         const int t = (int)(e & 4095u), k = (int)(e >> 12);
;         bf16x8 qr[8];
; #pragma unroll
;         for (int ks = 0; ks < 8; ++ks) qr[ks] = qn[ks];
;         if (qt + 8 < ntile) { const int idx = beg + (qt + 8) * 32 + r32; vn = idx < end; en = list[vn ? idx : beg]; moba_load_q(qn, P, (size_t)(b * SEQ + (int)(en & 4095u)), h, hi); }
.LBB0_941:
	s_or_b64 exec, exec, s[0:1]
	s_andn2_b64 vcc, exec, s[44:45]
	s_mov_b64 s[46:47], s[4:5]
	v_mov_b32_e32 v228, v227
	s_cbranch_vccz .LBB0_931

; __device__ __forceinline__ void moba_kv_item(LAS unsigned char* lds, const Ptrs& P, int bh, int n, int part, bool split) {
;     ...
;         for (int ks = 0; ks < 8; ++ks) qr[ks] = qn[ks];
;         if (qt + 8 < ntile) { const int idx = beg + (qt + 8) * 32 + r32; vn = idx < end; en = list[vn ? idx : beg]; moba_load_q(qn, P, (size_t)(b * SEQ + (int)(en & 4095u)), h, hi); }
;     ...
;         const float lt = l + __shfl_xor(l, 32); const float inv = __builtin_amdgcn_rcpf(lt);
;         if (valid) {
;             const size_t slot = ((size_t)bh * SEQ + t) * 3 + k;
;             if (hi == 0) *(f32x2*)(P.ML() + slot * 2) = (f32x2){m, lt};
.LBB0_952:
	s_waitcnt vmcnt(7)
	v_mov_b64_e32 v[178:179], v[146:147]
	s_waitcnt vmcnt(6)
	v_mov_b64_e32 v[182:183], v[150:151]
	s_waitcnt vmcnt(5)
	v_mov_b64_e32 v[186:187], v[154:155]
	s_waitcnt vmcnt(4)
	v_mov_b64_e32 v[190:191], v[158:159]
	s_waitcnt vmcnt(3)
	v_mov_b64_e32 v[194:195], v[162:163]
	s_waitcnt vmcnt(2)
	v_mov_b64_e32 v[198:199], v[166:167]
	s_waitcnt vmcnt(1)
	v_mov_b64_e32 v[202:203], v[170:171]
	s_waitcnt vmcnt(0)
	v_mov_b64_e32 v[206:207], v[174:175]
	v_mov_b64_e32 v[176:177], v[144:145]
	v_mov_b64_e32 v[180:181], v[148:149]
	v_mov_b64_e32 v[184:185], v[152:153]
	v_mov_b64_e32 v[188:189], v[156:157]
	v_mov_b64_e32 v[192:193], v[160:161]
	v_mov_b64_e32 v[196:197], v[164:165]
	v_mov_b64_e32 v[200:201], v[168:169]
	v_mov_b64_e32 v[204:205], v[172:173]
	ds_bpermute_b32 v1, v220, v229
	s_and_saveexec_b64 s[0:1], s[46:47]
	s_cbranch_execz .LBB0_941
	s_waitcnt lgkmcnt(0)
	v_add_f32_e32 v219, v229, v1
	v_lshrrev_b32_e32 v2, 12, v228
	v_or_b32_e32 v1, s24, v217
	v_mov_b32_e32 v3, v0
	v_mad_u64_u32 v[2:3], s[18:19], v1, 3, v[2:3]
	v_mad_i32_i24 v3, s25, 3, v3
	s_and_saveexec_b64 s[18:19], s[2:3]
	s_cbranch_execz .LBB0_940
	v_lshl_add_u64 v[4:5], v[2:3], 3, s[14:15]
	global_store_dwordx2 v[4:5], v[218:219], off
	s_branch .LBB0_940
